# combined: MLA loop without permlane swaps, V pieces in flight over the step barrier, static priority for waves 4-7; in-proj epilogue scale loads issued at unit start; serpentine MFMA order in the GEMM
# speedup vs baseline: 1.0044x; 1.0044x over previous
.LBB0_28:
	s_add_u32 s8, s56, 0xfff80080
	s_addc_u32 s12, s57, -1
	s_add_i32 s20, 0, 0x10000
	s_cmp_eq_u32 s63, 28
	s_cselect_b32 s13, s47, s12
	s_cselect_b32 s12, s51, s8
	v_add_u32_e32 v138, s20, v141
	v_add_u32_e32 v238, s20, v241
	s_cselect_b32 s59, s45, s62
	s_cselect_b32 s58, s60, s61
	s_add_i32 s8, 0, 0x14000
	ds_read_b128 v[144:147], v138
	ds_read_b128 v[148:151], v238
	ds_read_b128 v[152:155], v138 offset:2048
	ds_read_b128 v[156:159], v238 offset:2048
	v_add_u32_e32 v138, s8, v141
	v_add_u32_e32 v238, s8, v241
	ds_read_b128 v[160:163], v138
	ds_read_b128 v[164:167], v238
	ds_read_b128 v[168:171], v138 offset:2048
	ds_read_b128 v[172:175], v238 offset:2048
	v_lshl_add_u64 v[138:139], s[56:57], 0, v[134:135]
	s_add_i32 m0, s31, 0xc000
	ds_read_b128 v[176:179], v143
	ds_read_b128 v[180:183], v240
	ds_read_b128 v[186:189], v143 offset:2048
	ds_read_b128 v[192:195], v240 offset:2048
	ds_read_b128 v[196:199], v143 offset:4096
	ds_read_b128 v[214:217], v240 offset:4096
	ds_read_b128 v[218:221], v143 offset:6144
	ds_read_b128 v[222:225], v240 offset:6144
	global_load_lds_dwordx4 v[138:139], off
	v_lshl_add_u64 v[138:139], s[56:57], 0, v[136:137]
	s_add_i32 m0, s31, 0xe000
	s_nop 0
	global_load_lds_dwordx4 v[138:139], off
	s_waitcnt vmcnt(8)
	s_waitcnt lgkmcnt(0)
	s_barrier
	s_setprio 1
	s_waitcnt lgkmcnt(0)
	v_mfma_f32_16x16x32_bf16 v[124:127], v[144:147], v[176:179], v[124:127]
	v_mfma_f32_16x16x32_bf16 v[120:123], v[152:155], v[176:179], v[120:123]
	v_mfma_f32_16x16x32_bf16 v[108:111], v[152:155], v[186:189], v[108:111]
	v_mfma_f32_16x16x32_bf16 v[116:119], v[144:147], v[186:189], v[116:119]
	v_mfma_f32_16x16x32_bf16 v[100:103], v[144:147], v[196:199], v[100:103]
	v_mfma_f32_16x16x32_bf16 v[92:95], v[152:155], v[196:199], v[92:95]
	v_mfma_f32_16x16x32_bf16 v[76:79], v[152:155], v[218:221], v[76:79]
	v_mfma_f32_16x16x32_bf16 v[84:87], v[144:147], v[218:221], v[84:87]
	v_mfma_f32_16x16x32_bf16 v[124:127], v[148:151], v[180:183], v[124:127]
	v_mfma_f32_16x16x32_bf16 v[120:123], v[156:159], v[180:183], v[120:123]
	v_mfma_f32_16x16x32_bf16 v[108:111], v[156:159], v[192:195], v[108:111]
	v_mfma_f32_16x16x32_bf16 v[116:119], v[148:151], v[192:195], v[116:119]
	v_mfma_f32_16x16x32_bf16 v[100:103], v[148:151], v[214:217], v[100:103]
	v_mfma_f32_16x16x32_bf16 v[92:95], v[156:159], v[214:217], v[92:95]
	v_mfma_f32_16x16x32_bf16 v[76:79], v[156:159], v[222:225], v[76:79]
	v_mfma_f32_16x16x32_bf16 v[84:87], v[148:151], v[222:225], v[84:87]
	s_setprio 0
	s_setprio 1
	v_mfma_f32_16x16x32_bf16 v[112:115], v[160:163], v[176:179], v[112:115]
	v_mfma_f32_16x16x32_bf16 v[104:107], v[168:171], v[176:179], v[104:107]
	v_mfma_f32_16x16x32_bf16 v[88:91], v[168:171], v[186:189], v[88:91]
	v_mfma_f32_16x16x32_bf16 v[96:99], v[160:163], v[186:189], v[96:99]
	v_mfma_f32_16x16x32_bf16 v[80:83], v[160:163], v[196:199], v[80:83]
	v_mfma_f32_16x16x32_bf16 v[72:75], v[168:171], v[196:199], v[72:75]
	v_mfma_f32_16x16x32_bf16 v[64:67], v[168:171], v[218:221], v[64:67]
	v_mfma_f32_16x16x32_bf16 v[68:71], v[160:163], v[218:221], v[68:71]
	v_mfma_f32_16x16x32_bf16 v[112:115], v[164:167], v[180:183], v[112:115]
	v_mfma_f32_16x16x32_bf16 v[104:107], v[172:175], v[180:183], v[104:107]
	v_mfma_f32_16x16x32_bf16 v[88:91], v[172:175], v[192:195], v[88:91]
	v_mfma_f32_16x16x32_bf16 v[96:99], v[164:167], v[192:195], v[96:99]
	v_mfma_f32_16x16x32_bf16 v[80:83], v[164:167], v[214:217], v[80:83]
	v_mfma_f32_16x16x32_bf16 v[72:75], v[172:175], v[214:217], v[72:75]
	v_mfma_f32_16x16x32_bf16 v[64:67], v[172:175], v[222:225], v[64:67]
	v_mfma_f32_16x16x32_bf16 v[68:71], v[164:167], v[222:225], v[68:71]
	s_setprio 0
	s_barrier
	s_add_i32 s20, s20, s30
	v_lshl_add_u64 v[138:139], s[58:59], 0, v[184:185]
	s_mov_b32 m0, s20
	ds_read_b128 v[176:179], v143 offset:16384
	ds_read_b128 v[180:183], v240 offset:16384
	ds_read_b128 v[186:189], v143 offset:18432
	ds_read_b128 v[192:195], v240 offset:18432
	ds_read_b128 v[196:199], v143 offset:20480
	ds_read_b128 v[214:217], v240 offset:20480
	ds_read_b128 v[218:221], v143 offset:22528
	ds_read_b128 v[222:225], v240 offset:22528
	global_load_lds_dwordx4 v[138:139], off
	s_add_i32 m0, s20, 0x2000
	s_add_u32 s20, s58, 0x80000
	v_lshl_add_u64 v[200:201], s[58:59], 0, v[128:129]
	s_addc_u32 s21, s59, 0
	s_add_i32 s8, s8, s30
	global_load_lds_dwordx4 v[200:201], off
	v_lshl_add_u64 v[226:227], s[20:21], 0, v[184:185]
	s_mov_b32 m0, s8
	v_lshl_add_u64 v[228:229], s[12:13], 0, v[130:131]
	global_load_lds_dwordx4 v[226:227], off
	v_lshl_add_u64 v[226:227], s[20:21], 0, v[128:129]
	s_add_i32 m0, s8, 0x2000
	s_nop 0
	global_load_lds_dwordx4 v[226:227], off
	v_lshl_add_u64 v[226:227], s[12:13], 0, v[132:133]
	s_mov_b32 m0, s31
	s_nop 0
	global_load_lds_dwordx4 v[226:227], off
	s_mov_b32 m0, s34
	s_nop 0
	global_load_lds_dwordx4 v[228:229], off
	s_waitcnt vmcnt(8)
	s_waitcnt lgkmcnt(0)
	s_barrier
	s_setprio 1
	s_waitcnt lgkmcnt(0)
	v_mfma_f32_16x16x32_bf16 v[60:63], v[144:147], v[176:179], v[60:63]
	v_mfma_f32_16x16x32_bf16 v[56:59], v[152:155], v[176:179], v[56:59]
	v_mfma_f32_16x16x32_bf16 v[44:47], v[152:155], v[186:189], v[44:47]
	v_mfma_f32_16x16x32_bf16 v[52:55], v[144:147], v[186:189], v[52:55]
	v_mfma_f32_16x16x32_bf16 v[36:39], v[144:147], v[196:199], v[36:39]
	v_mfma_f32_16x16x32_bf16 v[28:31], v[152:155], v[196:199], v[28:31]
	v_mfma_f32_16x16x32_bf16 v[12:15], v[152:155], v[218:221], v[12:15]
	v_mfma_f32_16x16x32_bf16 v[20:23], v[144:147], v[218:221], v[20:23]
	v_mfma_f32_16x16x32_bf16 v[60:63], v[148:151], v[180:183], v[60:63]
	v_mfma_f32_16x16x32_bf16 v[56:59], v[156:159], v[180:183], v[56:59]
	v_mfma_f32_16x16x32_bf16 v[44:47], v[156:159], v[192:195], v[44:47]
	v_mfma_f32_16x16x32_bf16 v[52:55], v[148:151], v[192:195], v[52:55]
	v_mfma_f32_16x16x32_bf16 v[36:39], v[148:151], v[214:217], v[36:39]
	v_mfma_f32_16x16x32_bf16 v[28:31], v[156:159], v[214:217], v[28:31]
	v_mfma_f32_16x16x32_bf16 v[12:15], v[156:159], v[222:225], v[12:15]
	v_mfma_f32_16x16x32_bf16 v[20:23], v[148:151], v[222:225], v[20:23]
	s_setprio 0
	s_setprio 1
	v_mfma_f32_16x16x32_bf16 v[48:51], v[160:163], v[176:179], v[48:51]
	v_mfma_f32_16x16x32_bf16 v[40:43], v[168:171], v[176:179], v[40:43]
	v_mfma_f32_16x16x32_bf16 v[24:27], v[168:171], v[186:189], v[24:27]
	v_mfma_f32_16x16x32_bf16 v[32:35], v[160:163], v[186:189], v[32:35]
	v_mfma_f32_16x16x32_bf16 v[16:19], v[160:163], v[196:199], v[16:19]
	v_mfma_f32_16x16x32_bf16 v[8:11], v[168:171], v[196:199], v[8:11]
	v_mfma_f32_16x16x32_bf16 v[0:3], v[168:171], v[218:221], v[0:3]
	v_mfma_f32_16x16x32_bf16 v[4:7], v[160:163], v[218:221], v[4:7]
	v_mfma_f32_16x16x32_bf16 v[48:51], v[164:167], v[180:183], v[48:51]
	v_mfma_f32_16x16x32_bf16 v[40:43], v[172:175], v[180:183], v[40:43]
	v_mfma_f32_16x16x32_bf16 v[24:27], v[172:175], v[192:195], v[24:27]
	v_mfma_f32_16x16x32_bf16 v[32:35], v[164:167], v[192:195], v[32:35]
	v_mfma_f32_16x16x32_bf16 v[16:19], v[164:167], v[214:217], v[16:19]
	v_mfma_f32_16x16x32_bf16 v[8:11], v[172:175], v[214:217], v[8:11]
	v_mfma_f32_16x16x32_bf16 v[0:3], v[172:175], v[222:225], v[0:3]
	v_mfma_f32_16x16x32_bf16 v[4:7], v[164:167], v[222:225], v[4:7]
	s_setprio 0
	s_barrier
	s_add_i32 s8, 0, 0x18000
	s_add_i32 s20, 0, 0x1c000
	v_add_u32_e32 v156, s8, v141
	v_add_u32_e32 v238, s8, v241
	v_add_u32_e32 v172, s20, v141
	v_add_u32_e32 v239, s20, v241
	ds_read_b128 v[144:147], v156
	ds_read_b128 v[148:151], v238
	ds_read_b128 v[152:155], v156 offset:2048
	ds_read_b128 v[156:159], v238 offset:2048
	ds_read_b128 v[160:163], v172
	ds_read_b128 v[164:167], v239
	ds_read_b128 v[168:171], v172 offset:2048
	ds_read_b128 v[172:175], v239 offset:2048
	s_add_u32 s12, s12, 0x80000
	s_addc_u32 s13, s13, 0
	s_mov_b32 m0, s35
	v_lshl_add_u64 v[230:231], s[12:13], 0, v[132:133]
	ds_read_b128 v[176:179], v143 offset:32768
	ds_read_b128 v[180:183], v240 offset:32768
	ds_read_b128 v[186:189], v143 offset:34816
	ds_read_b128 v[192:195], v240 offset:34816
	ds_read_b128 v[196:199], v143 offset:36864
	ds_read_b128 v[214:217], v240 offset:36864
	ds_read_b128 v[218:221], v143 offset:38912
	ds_read_b128 v[222:225], v240 offset:38912
	global_load_lds_dwordx4 v[230:231], off
	v_lshl_add_u64 v[230:231], s[12:13], 0, v[130:131]
	s_mov_b32 m0, s36
	s_nop 0
	global_load_lds_dwordx4 v[230:231], off
	s_waitcnt vmcnt(8)
	s_waitcnt lgkmcnt(0)
	s_barrier
	s_setprio 1
	s_waitcnt lgkmcnt(0)
	v_mfma_f32_16x16x32_bf16 v[124:127], v[144:147], v[176:179], v[124:127]
	v_mfma_f32_16x16x32_bf16 v[120:123], v[152:155], v[176:179], v[120:123]
	v_mfma_f32_16x16x32_bf16 v[108:111], v[152:155], v[186:189], v[108:111]
	v_mfma_f32_16x16x32_bf16 v[116:119], v[144:147], v[186:189], v[116:119]
	v_mfma_f32_16x16x32_bf16 v[100:103], v[144:147], v[196:199], v[100:103]
	v_mfma_f32_16x16x32_bf16 v[92:95], v[152:155], v[196:199], v[92:95]
	v_mfma_f32_16x16x32_bf16 v[76:79], v[152:155], v[218:221], v[76:79]
	v_mfma_f32_16x16x32_bf16 v[84:87], v[144:147], v[218:221], v[84:87]
	v_mfma_f32_16x16x32_bf16 v[124:127], v[148:151], v[180:183], v[124:127]
	v_mfma_f32_16x16x32_bf16 v[120:123], v[156:159], v[180:183], v[120:123]
	v_mfma_f32_16x16x32_bf16 v[108:111], v[156:159], v[192:195], v[108:111]
	v_mfma_f32_16x16x32_bf16 v[116:119], v[148:151], v[192:195], v[116:119]
	v_mfma_f32_16x16x32_bf16 v[100:103], v[148:151], v[214:217], v[100:103]
	v_mfma_f32_16x16x32_bf16 v[92:95], v[156:159], v[214:217], v[92:95]
	v_mfma_f32_16x16x32_bf16 v[76:79], v[156:159], v[222:225], v[76:79]
	v_mfma_f32_16x16x32_bf16 v[84:87], v[148:151], v[222:225], v[84:87]
	s_setprio 0
	s_setprio 1
	v_mfma_f32_16x16x32_bf16 v[112:115], v[160:163], v[176:179], v[112:115]
	v_mfma_f32_16x16x32_bf16 v[104:107], v[168:171], v[176:179], v[104:107]
	v_mfma_f32_16x16x32_bf16 v[88:91], v[168:171], v[186:189], v[88:91]
	v_mfma_f32_16x16x32_bf16 v[96:99], v[160:163], v[186:189], v[96:99]
	v_mfma_f32_16x16x32_bf16 v[80:83], v[160:163], v[196:199], v[80:83]
	v_mfma_f32_16x16x32_bf16 v[72:75], v[168:171], v[196:199], v[72:75]
	v_mfma_f32_16x16x32_bf16 v[64:67], v[168:171], v[218:221], v[64:67]
	v_mfma_f32_16x16x32_bf16 v[68:71], v[160:163], v[218:221], v[68:71]
	v_mfma_f32_16x16x32_bf16 v[112:115], v[164:167], v[180:183], v[112:115]
	v_mfma_f32_16x16x32_bf16 v[104:107], v[172:175], v[180:183], v[104:107]
	v_mfma_f32_16x16x32_bf16 v[88:91], v[172:175], v[192:195], v[88:91]
	v_mfma_f32_16x16x32_bf16 v[96:99], v[164:167], v[192:195], v[96:99]
	v_mfma_f32_16x16x32_bf16 v[80:83], v[164:167], v[214:217], v[80:83]
	v_mfma_f32_16x16x32_bf16 v[72:75], v[172:175], v[214:217], v[72:75]
	v_mfma_f32_16x16x32_bf16 v[64:67], v[172:175], v[222:225], v[64:67]
	v_mfma_f32_16x16x32_bf16 v[68:71], v[164:167], v[222:225], v[68:71]
	s_setprio 0
	s_barrier
	s_add_i32 s8, s8, s30
	v_lshl_add_u64 v[138:139], v[138:139], 0, s[26:27]
	s_mov_b32 m0, s8
	ds_read_b128 v[176:179], v143 offset:49152
	ds_read_b128 v[180:183], v240 offset:49152
	ds_read_b128 v[186:189], v143 offset:51200
	ds_read_b128 v[192:195], v240 offset:51200
	ds_read_b128 v[196:199], v143 offset:53248
	ds_read_b128 v[214:217], v240 offset:53248
	ds_read_b128 v[218:221], v143 offset:55296
	ds_read_b128 v[222:225], v240 offset:55296
	global_load_lds_dwordx4 v[138:139], off
	s_add_i32 m0, s8, 0x2000
	s_add_u32 s12, s58, 0x80080
	v_lshl_add_u64 v[138:139], v[200:201], 0, s[26:27]
	s_addc_u32 s13, s59, 0
	s_add_i32 s8, s20, s30
	global_load_lds_dwordx4 v[138:139], off
	v_lshl_add_u64 v[138:139], s[12:13], 0, v[184:185]
	s_mov_b32 m0, s8
	s_nop 0
	global_load_lds_dwordx4 v[138:139], off
	v_lshl_add_u64 v[138:139], s[12:13], 0, v[128:129]
	s_add_i32 m0, s8, 0x2000
	s_nop 0
	global_load_lds_dwordx4 v[138:139], off
	v_lshl_add_u64 v[138:139], v[226:227], 0, s[26:27]
	s_mov_b32 m0, s38
	s_nop 0
	global_load_lds_dwordx4 v[138:139], off
	v_lshl_add_u64 v[138:139], v[228:229], 0, s[26:27]
	s_mov_b32 m0, s39
	s_nop 0
	global_load_lds_dwordx4 v[138:139], off
	s_waitcnt vmcnt(8)
	s_waitcnt lgkmcnt(0)
	s_barrier
	s_setprio 1
	s_waitcnt lgkmcnt(0)
	v_mfma_f32_16x16x32_bf16 v[60:63], v[144:147], v[176:179], v[60:63]
	v_mfma_f32_16x16x32_bf16 v[56:59], v[152:155], v[176:179], v[56:59]
	v_mfma_f32_16x16x32_bf16 v[44:47], v[152:155], v[186:189], v[44:47]
	v_mfma_f32_16x16x32_bf16 v[52:55], v[144:147], v[186:189], v[52:55]
	v_mfma_f32_16x16x32_bf16 v[36:39], v[144:147], v[196:199], v[36:39]
	v_mfma_f32_16x16x32_bf16 v[28:31], v[152:155], v[196:199], v[28:31]
	v_mfma_f32_16x16x32_bf16 v[12:15], v[152:155], v[218:221], v[12:15]
	v_mfma_f32_16x16x32_bf16 v[20:23], v[144:147], v[218:221], v[20:23]
	v_mfma_f32_16x16x32_bf16 v[60:63], v[148:151], v[180:183], v[60:63]
	v_mfma_f32_16x16x32_bf16 v[56:59], v[156:159], v[180:183], v[56:59]
	v_mfma_f32_16x16x32_bf16 v[44:47], v[156:159], v[192:195], v[44:47]
	v_mfma_f32_16x16x32_bf16 v[52:55], v[148:151], v[192:195], v[52:55]
	v_mfma_f32_16x16x32_bf16 v[36:39], v[148:151], v[214:217], v[36:39]
	v_mfma_f32_16x16x32_bf16 v[28:31], v[156:159], v[214:217], v[28:31]
	v_mfma_f32_16x16x32_bf16 v[12:15], v[156:159], v[222:225], v[12:15]
	v_mfma_f32_16x16x32_bf16 v[20:23], v[148:151], v[222:225], v[20:23]
	s_setprio 0
	s_setprio 1
	v_mfma_f32_16x16x32_bf16 v[48:51], v[160:163], v[176:179], v[48:51]
	v_mfma_f32_16x16x32_bf16 v[40:43], v[168:171], v[176:179], v[40:43]
	v_mfma_f32_16x16x32_bf16 v[24:27], v[168:171], v[186:189], v[24:27]
	v_mfma_f32_16x16x32_bf16 v[32:35], v[160:163], v[186:189], v[32:35]
	v_mfma_f32_16x16x32_bf16 v[16:19], v[160:163], v[196:199], v[16:19]
	v_mfma_f32_16x16x32_bf16 v[8:11], v[168:171], v[196:199], v[8:11]
	v_mfma_f32_16x16x32_bf16 v[0:3], v[168:171], v[218:221], v[0:3]
	v_mfma_f32_16x16x32_bf16 v[4:7], v[160:163], v[218:221], v[4:7]
	v_mfma_f32_16x16x32_bf16 v[48:51], v[164:167], v[180:183], v[48:51]
	v_mfma_f32_16x16x32_bf16 v[40:43], v[172:175], v[180:183], v[40:43]
	v_mfma_f32_16x16x32_bf16 v[24:27], v[172:175], v[192:195], v[24:27]
	v_mfma_f32_16x16x32_bf16 v[32:35], v[164:167], v[192:195], v[32:35]
	v_mfma_f32_16x16x32_bf16 v[16:19], v[164:167], v[214:217], v[16:19]
	v_mfma_f32_16x16x32_bf16 v[8:11], v[172:175], v[214:217], v[8:11]
	v_mfma_f32_16x16x32_bf16 v[0:3], v[172:175], v[222:225], v[0:3]
	v_mfma_f32_16x16x32_bf16 v[4:7], v[164:167], v[222:225], v[4:7]
	s_setprio 0
	s_barrier
	s_add_i32 s63, s63, 2
	s_add_u32 s56, s56, 0x100
	s_addc_u32 s57, s57, 0
	s_add_u32 s61, s61, 0x100
	s_addc_u32 s62, s62, 0
	s_cmp_gt_u32 s63, 29
	s_cbranch_scc0 .LBB0_28
	s_and_b64 vcc, exec, s[42:43]
	s_cbranch_vccz .LBB0_31
	s_barrier

.LBB0_42:
	v_add_u32_e32 v166, 0x8000, v166
	v_add_u32_e32 v167, 0x8000, v168
	v_add_u32_e32 v168, 0x8000, v170
	v_add_u32_e32 v169, 0x8000, v172
	v_add_u32_e32 v170, 0x8000, v174
	v_add_u32_e32 v171, 0x8000, v176
	v_add_u32_e32 v172, 0x8000, v178
	v_add_u32_e32 v173, 0x8000, v180
	v_mov_b32_e32 v174, v183
	v_mov_b32_e32 v175, v193
	v_mov_b32_e32 v176, v195
	v_mov_b32_e32 v177, v197
	v_mov_b32_e32 v178, v140
	v_mov_b32_e32 v179, v142
	v_add_u32_e32 v180, 0x100, v138
	v_add_u32_e32 v181, 0x180, v138
	v_mov_b32_e32 v182, v136
	s_add_u32 s98, s74, 0x13480000
	s_addc_u32 s99, s75, 0
	s_add_u32 s100, s74, 0xae04000
	s_addc_u32 s101, s75, 0
	v_mov_b32_e32 v144, v158
	v_mov_b32_e32 v145, v159
	v_mov_b32_e32 v146, v156
	v_mov_b32_e32 v147, v157
	v_mov_b32_e32 v148, v154
	v_mov_b32_e32 v149, v155
	v_mov_b32_e32 v150, v152
	v_mov_b32_e32 v151, v153
	v_mov_b32_e32 v152, v134
	v_mov_b32_e32 v153, v135
	v_mov_b32_e32 v154, v132
	v_mov_b32_e32 v155, v133
	v_mov_b32_e32 v156, v130
	v_mov_b32_e32 v157, v131
	v_mov_b32_e32 v158, v128
	v_mov_b32_e32 v159, v129
	v_mbcnt_lo_u32_b32 v192, -1, 0
	v_mbcnt_hi_u32_b32 v192, -1, v192
	v_and_b32_e32 v192, 32, v192
	v_mad_u32_u24 v192, v192, 56, v161
	v_mov_b32_e32 v242, v198
	v_sub_f32_e32 v198, 0, v222
	v_sub_f32_e32 v199, 0, v222
	v_sub_f32_e32 v200, 0, v222
	v_sub_f32_e32 v201, 0, v222
	v_sub_f32_e32 v202, 0, v222
	v_sub_f32_e32 v203, 0, v222
	v_sub_f32_e32 v204, 0, v222
	v_sub_f32_e32 v205, 0, v222
	v_sub_f32_e32 v206, 0, v222
	v_sub_f32_e32 v207, 0, v222
	v_sub_f32_e32 v208, 0, v222
	v_sub_f32_e32 v209, 0, v222
	v_sub_f32_e32 v210, 0, v222
	v_sub_f32_e32 v211, 0, v222
	v_sub_f32_e32 v212, 0, v222
	v_sub_f32_e32 v213, 0, v222
	v_mov_b32_e32 v128, v236
	v_mov_b32_e32 v129, v238
	v_mov_b32_e32 v130, v234
	v_mov_b32_e32 v131, v237
	v_mov_b32_e32 v132, v233
	v_mov_b32_e32 v133, v235
	v_mov_b32_e32 v134, v231
	v_mov_b32_e32 v135, v232
	v_mov_b32_e32 v136, v228
	v_mov_b32_e32 v137, v230
	v_mov_b32_e32 v138, v227
	v_mov_b32_e32 v139, v229
	v_mov_b32_e32 v140, v224
	v_mov_b32_e32 v141, v226
	v_mov_b32_e32 v142, v223
	v_mov_b32_e32 v143, v225
	v_readfirstlane_b32 s8, v191
	s_nop 3
	s_lshr_b32 s8, s8, 6
	s_cmp_ge_u32 s8, 4
	s_cbranch_scc0 .Lmla_prio
	s_setprio 1

.Lmla_nors_B:
	s_add_i32 s8, s14, 1
	s_cmp_lg_u32 s14, 2
	s_cselect_b32 s52, s8, 0
	s_add_i32 s8, s15, 1
	s_cmp_lg_u32 s15, 2
	s_cselect_b32 s49, s8, 0
	s_waitcnt vmcnt(2) lgkmcnt(0)
	s_barrier
	s_add_i32 s48, s48, 2
	s_cmp_lt_u32 s48, 61
	s_cbranch_scc1 .Lmla_loop
	v_mov_b32_e32 v236, v128
	v_mov_b32_e32 v238, v129
	v_mov_b32_e32 v234, v130
	v_mov_b32_e32 v237, v131
	v_mov_b32_e32 v233, v132
	v_mov_b32_e32 v235, v133
	v_mov_b32_e32 v231, v134
	v_mov_b32_e32 v232, v135
	v_mov_b32_e32 v228, v136
	v_mov_b32_e32 v230, v137
	v_mov_b32_e32 v227, v138
	v_mov_b32_e32 v229, v139
	v_mov_b32_e32 v224, v140
	v_mov_b32_e32 v226, v141
	v_mov_b32_e32 v223, v142
	v_mov_b32_e32 v225, v143
	v_mov_b32_e32 v134, v152
	v_mov_b32_e32 v135, v153
	v_mov_b32_e32 v132, v154
	v_mov_b32_e32 v133, v155
	v_mov_b32_e32 v130, v156
	v_mov_b32_e32 v131, v157
	v_mov_b32_e32 v128, v158
	v_mov_b32_e32 v129, v159
	v_mov_b32_e32 v158, v144
	v_mov_b32_e32 v159, v145
	v_mov_b32_e32 v156, v146
	v_mov_b32_e32 v157, v147
	v_mov_b32_e32 v154, v148
	v_mov_b32_e32 v155, v149
	v_mov_b32_e32 v152, v150
	v_mov_b32_e32 v153, v151
	s_setprio 0
	s_waitcnt vmcnt(0)
	s_barrier
	v_sub_f32_e32 v222, 0, v198
	v_mov_b32_e32 v144, v242
	v_mov_b32_e32 v198, v242
	v_add_u32_e32 v199, 0x8000, v166
	v_add_u32_e32 v200, 0x8000, v167
	v_add_u32_e32 v201, 0x8000, v168
	v_add_u32_e32 v202, 0x8000, v169
	v_add_u32_e32 v214, 0x8000, v170
	v_add_u32_e32 v215, 0x8000, v171
	v_add_u32_e32 v216, 0x8000, v172
	v_add_u32_e32 v217, 0x8000, v173
	v_add_u32_e32 v219, 0x2000, v174
	v_add_u32_e32 v218, 0x2000, v175
	v_add_u32_e32 v220, 0x2000, v176
	v_add_u32_e32 v221, 0x2000, v177
	v_mov_b32_e32 v203, v191
	v_mov_b32_e32 v204, 0x358637bd
	v_mov_b32_e32 v205, 0x260
	v_mov_b32_e32 v206, 1
	v_mov_b32_e32 v207, 0xf149f2ca
	v_mbcnt_lo_u32_b32 v208, -1, 0
	v_mbcnt_hi_u32_b32 v208, -1, v208
	v_mov_b32_e32 v209, 0x1450
	v_mov_b64_e32 v[210:211], 0x400
	v_mov_b32_e32 v212, 0x1c70
	v_and_b32_e32 v213, 63, v191
	v_mov_b32_e32 v242, 0
	v_mov_b32_e32 v243, 0
	v_mov_b32_e32 v244, 0
	v_mov_b32_e32 v245, 0

.LBB0_179:
	s_lshl_b32 s6, s16, 8
	s_add_i32 s6, s6, s96
	v_add_u32_e32 v238, s6, v146
	v_ashrrev_i32_e32 v239, 31, v238
	v_lshl_add_u64 v[238:239], v[238:239], 2, s[60:61]
	global_load_dword v246, v[238:239], off
	global_load_dword v247, v[238:239], off offset:64
	global_load_dword v248, v[238:239], off offset:128
	global_load_dword v249, v[238:239], off offset:192
	global_load_dword v250, v[238:239], off offset:512
	global_load_dword v251, v[238:239], off offset:576
	global_load_dword v252, v[238:239], off offset:640
	global_load_dword v253, v[238:239], off offset:704
	v_readlane_b32 s48, v254, 2
	s_add_i32 s36, s36, 1
	v_readlane_b32 s50, v254, 4
	s_mul_i32 s6, s36, s3
	s_mul_hi_u32 s7, s36, s50
	s_add_i32 s7, s7, s6
	s_mul_i32 s6, s36, s50
	s_add_u32 s6, s6, s2
	s_addc_u32 s7, s7, s81
	s_waitcnt lgkmcnt(0)
	v_mov_b64_e32 v[0:1], 0xa00
	v_cmp_lt_i64_e64 s[42:43], s[6:7], v[0:1]
	v_mov_b64_e32 v[0:1], 0x9ff
	v_cmp_gt_i64_e32 vcc, s[6:7], v[0:1]
	v_readlane_b32 s49, v254, 3
	v_readlane_b32 s51, v254, 5
	s_cbranch_vccnz .LBB0_181
	s_ashr_i32 s7, s6, 31
	s_lshr_b32 s7, s7, 29
	s_add_i32 s7, s6, s7
	s_ashr_i32 s8, s7, 3
	s_and_b32 s7, s7, -8
	s_sub_i32 s6, s6, s7
	s_cmp_lt_i32 s6, 0
	s_movk_i32 s7, 0x141
	s_cselect_b32 s7, s7, 0x140
	s_mul_i32 s6, s6, s7
	s_add_i32 s6, s6, s8
	s_mul_hi_i32 s7, s6, 0x66666667
	s_lshr_b32 s8, s7, 31
	s_ashr_i32 s7, s7, 6
	s_add_i32 s7, s7, s8
	s_lshl_b32 s8, s7, 3
	s_sub_i32 s12, 0x80, s8
	s_min_i32 s12, s12, 8
	s_abs_i32 s13, s12
	v_cvt_f32_u32_e32 v0, s13
	s_sub_i32 s21, 0, s13
	s_mulk_i32 s7, 0xa0
	s_sub_i32 s6, s6, s7
	v_rcp_iflag_f32_e32 v0, v0
	s_abs_i32 s7, s6
	s_xor_b32 s20, s6, s12
	s_ashr_i32 s20, s20, 31
	v_mul_f32_e32 v0, 0x4f7ffffe, v0
	v_cvt_u32_f32_e32 v0, v0
	s_nop 0
	v_readfirstlane_b32 s33, v0
	s_mul_i32 s21, s21, s33
	s_mul_hi_u32 s21, s33, s21
	s_add_i32 s33, s33, s21
	s_mul_hi_u32 s21, s7, s33
	s_mul_i32 s33, s21, s13
	s_sub_i32 s7, s7, s33
	s_add_i32 s37, s21, 1
	s_sub_i32 s33, s7, s13
	s_cmp_ge_u32 s7, s13
	s_cselect_b32 s21, s37, s21
	s_cselect_b32 s7, s33, s7
	s_add_i32 s33, s21, 1
	s_cmp_ge_u32 s7, s13
	s_cselect_b32 s7, s33, s21
	s_xor_b32 s7, s7, s20
	s_sub_i32 s64, s7, s20
	s_mul_i32 s7, s64, s12
	s_sub_i32 s6, s6, s7
	s_add_i32 s66, s8, s6

.LBB0_182:
	s_add_u32 s8, s14, 0xfff80080
	s_addc_u32 s12, s15, -1
	s_add_i32 s20, 0, 0x10000
	s_cmp_eq_u32 s51, 28
	s_cselect_b32 s13, s37, s12
	s_cselect_b32 s12, s46, s8
	s_cselect_b32 s45, s47, s50
	s_cselect_b32 s44, s48, s49
	s_add_i32 s8, 0, 0x14000
	v_add_u32_e32 v154, s20, v147
	v_add_u32_e32 v238, s20, v241
	v_add_u32_e32 v170, s8, v147
	v_add_u32_e32 v239, s8, v241
	ds_read_b128 v[138:141], v154
	ds_read_b128 v[142:145], v238
	ds_read_b128 v[150:153], v154 offset:2048
	ds_read_b128 v[154:157], v238 offset:2048
	ds_read_b128 v[158:161], v170
	ds_read_b128 v[162:165], v239
	ds_read_b128 v[166:169], v170 offset:2048
	ds_read_b128 v[170:173], v239 offset:2048
	v_lshl_add_u64 v[182:183], s[14:15], 0, v[134:135]
	s_add_i32 m0, s30, 0xc000
	ds_read_b128 v[174:177], v149
	ds_read_b128 v[178:181], v240
	ds_read_b128 v[192:195], v149 offset:2048
	ds_read_b128 v[196:199], v240 offset:2048
	ds_read_b128 v[214:217], v149 offset:4096
	ds_read_b128 v[218:221], v240 offset:4096
	ds_read_b128 v[222:225], v149 offset:6144
	ds_read_b128 v[226:229], v240 offset:6144
	global_load_lds_dwordx4 v[182:183], off
	v_lshl_add_u64 v[182:183], s[14:15], 0, v[136:137]
	s_add_i32 m0, s30, 0xe000
	s_nop 0
	global_load_lds_dwordx4 v[182:183], off
	s_waitcnt vmcnt(8)
	s_waitcnt lgkmcnt(0)
	s_barrier
	s_setprio 1
	s_waitcnt lgkmcnt(0)
	v_mfma_f32_16x16x32_bf16 v[124:127], v[138:141], v[174:177], v[124:127]
	v_mfma_f32_16x16x32_bf16 v[120:123], v[150:153], v[174:177], v[120:123]
	v_mfma_f32_16x16x32_bf16 v[104:107], v[150:153], v[192:195], v[104:107]
	v_mfma_f32_16x16x32_bf16 v[108:111], v[138:141], v[192:195], v[108:111]
	v_mfma_f32_16x16x32_bf16 v[92:95], v[138:141], v[214:217], v[92:95]
	v_mfma_f32_16x16x32_bf16 v[88:91], v[150:153], v[214:217], v[88:91]
	v_mfma_f32_16x16x32_bf16 v[72:75], v[150:153], v[222:225], v[72:75]
	v_mfma_f32_16x16x32_bf16 v[76:79], v[138:141], v[222:225], v[76:79]
	v_mfma_f32_16x16x32_bf16 v[124:127], v[142:145], v[178:181], v[124:127]
	v_mfma_f32_16x16x32_bf16 v[120:123], v[154:157], v[178:181], v[120:123]
	v_mfma_f32_16x16x32_bf16 v[104:107], v[154:157], v[196:199], v[104:107]
	v_mfma_f32_16x16x32_bf16 v[108:111], v[142:145], v[196:199], v[108:111]
	v_mfma_f32_16x16x32_bf16 v[92:95], v[142:145], v[218:221], v[92:95]
	v_mfma_f32_16x16x32_bf16 v[88:91], v[154:157], v[218:221], v[88:91]
	v_mfma_f32_16x16x32_bf16 v[72:75], v[154:157], v[226:229], v[72:75]
	v_mfma_f32_16x16x32_bf16 v[76:79], v[142:145], v[226:229], v[76:79]
	s_setprio 0
	s_setprio 1
	v_mfma_f32_16x16x32_bf16 v[116:119], v[158:161], v[174:177], v[116:119]
	v_mfma_f32_16x16x32_bf16 v[112:115], v[166:169], v[174:177], v[112:115]
	v_mfma_f32_16x16x32_bf16 v[96:99], v[166:169], v[192:195], v[96:99]
	v_mfma_f32_16x16x32_bf16 v[100:103], v[158:161], v[192:195], v[100:103]
	v_mfma_f32_16x16x32_bf16 v[84:87], v[158:161], v[214:217], v[84:87]
	v_mfma_f32_16x16x32_bf16 v[80:83], v[166:169], v[214:217], v[80:83]
	v_mfma_f32_16x16x32_bf16 v[64:67], v[166:169], v[222:225], v[64:67]
	v_mfma_f32_16x16x32_bf16 v[68:71], v[158:161], v[222:225], v[68:71]
	v_mfma_f32_16x16x32_bf16 v[116:119], v[162:165], v[178:181], v[116:119]
	v_mfma_f32_16x16x32_bf16 v[112:115], v[170:173], v[178:181], v[112:115]
	v_mfma_f32_16x16x32_bf16 v[96:99], v[170:173], v[196:199], v[96:99]
	v_mfma_f32_16x16x32_bf16 v[100:103], v[162:165], v[196:199], v[100:103]
	v_mfma_f32_16x16x32_bf16 v[84:87], v[162:165], v[218:221], v[84:87]
	v_mfma_f32_16x16x32_bf16 v[80:83], v[170:173], v[218:221], v[80:83]
	v_mfma_f32_16x16x32_bf16 v[64:67], v[170:173], v[226:229], v[64:67]
	v_mfma_f32_16x16x32_bf16 v[68:71], v[162:165], v[226:229], v[68:71]
	s_setprio 0
	s_barrier
	s_add_i32 s20, s20, s25
	v_lshl_add_u64 v[182:183], s[44:45], 0, v[184:185]
	s_mov_b32 m0, s20
	ds_read_b128 v[174:177], v149 offset:16384
	ds_read_b128 v[178:181], v240 offset:16384
	ds_read_b128 v[192:195], v149 offset:18432
	ds_read_b128 v[196:199], v240 offset:18432
	ds_read_b128 v[214:217], v149 offset:20480
	ds_read_b128 v[218:221], v240 offset:20480
	ds_read_b128 v[222:225], v149 offset:22528
	ds_read_b128 v[226:229], v240 offset:22528
	global_load_lds_dwordx4 v[182:183], off
	s_add_i32 m0, s20, 0x2000
	s_add_u32 s20, s44, 0x80000
	v_lshl_add_u64 v[186:187], s[44:45], 0, v[128:129]
	s_addc_u32 s21, s45, 0
	s_add_i32 s8, s8, s25
	global_load_lds_dwordx4 v[186:187], off
	v_lshl_add_u64 v[188:189], s[20:21], 0, v[184:185]
	s_mov_b32 m0, s8
	v_lshl_add_u64 v[200:201], s[12:13], 0, v[130:131]
	global_load_lds_dwordx4 v[188:189], off
	v_lshl_add_u64 v[188:189], s[20:21], 0, v[128:129]
	s_add_i32 m0, s8, 0x2000
	s_nop 0
	global_load_lds_dwordx4 v[188:189], off
	v_lshl_add_u64 v[188:189], s[12:13], 0, v[132:133]
	s_mov_b32 m0, s30
	s_nop 0
	global_load_lds_dwordx4 v[188:189], off
	s_mov_b32 m0, s31
	s_nop 0
	global_load_lds_dwordx4 v[200:201], off
	s_waitcnt vmcnt(8)
	s_waitcnt lgkmcnt(0)
	s_barrier
	s_setprio 1
	s_waitcnt lgkmcnt(0)
	v_mfma_f32_16x16x32_bf16 v[60:63], v[138:141], v[174:177], v[60:63]
	v_mfma_f32_16x16x32_bf16 v[56:59], v[150:153], v[174:177], v[56:59]
	v_mfma_f32_16x16x32_bf16 v[40:43], v[150:153], v[192:195], v[40:43]
	v_mfma_f32_16x16x32_bf16 v[44:47], v[138:141], v[192:195], v[44:47]
	v_mfma_f32_16x16x32_bf16 v[28:31], v[138:141], v[214:217], v[28:31]
	v_mfma_f32_16x16x32_bf16 v[24:27], v[150:153], v[214:217], v[24:27]
	v_mfma_f32_16x16x32_bf16 v[8:11], v[150:153], v[222:225], v[8:11]
	v_mfma_f32_16x16x32_bf16 v[12:15], v[138:141], v[222:225], v[12:15]
	v_mfma_f32_16x16x32_bf16 v[60:63], v[142:145], v[178:181], v[60:63]
	v_mfma_f32_16x16x32_bf16 v[56:59], v[154:157], v[178:181], v[56:59]
	v_mfma_f32_16x16x32_bf16 v[40:43], v[154:157], v[196:199], v[40:43]
	v_mfma_f32_16x16x32_bf16 v[44:47], v[142:145], v[196:199], v[44:47]
	v_mfma_f32_16x16x32_bf16 v[28:31], v[142:145], v[218:221], v[28:31]
	v_mfma_f32_16x16x32_bf16 v[24:27], v[154:157], v[218:221], v[24:27]
	v_mfma_f32_16x16x32_bf16 v[8:11], v[154:157], v[226:229], v[8:11]
	v_mfma_f32_16x16x32_bf16 v[12:15], v[142:145], v[226:229], v[12:15]
	s_setprio 0
	s_setprio 1
	v_mfma_f32_16x16x32_bf16 v[52:55], v[158:161], v[174:177], v[52:55]
	v_mfma_f32_16x16x32_bf16 v[48:51], v[166:169], v[174:177], v[48:51]
	v_mfma_f32_16x16x32_bf16 v[32:35], v[166:169], v[192:195], v[32:35]
	v_mfma_f32_16x16x32_bf16 v[36:39], v[158:161], v[192:195], v[36:39]
	v_mfma_f32_16x16x32_bf16 v[20:23], v[158:161], v[214:217], v[20:23]
	v_mfma_f32_16x16x32_bf16 v[16:19], v[166:169], v[214:217], v[16:19]
	v_mfma_f32_16x16x32_bf16 v[0:3], v[166:169], v[222:225], v[0:3]
	v_mfma_f32_16x16x32_bf16 v[4:7], v[158:161], v[222:225], v[4:7]
	v_mfma_f32_16x16x32_bf16 v[52:55], v[162:165], v[178:181], v[52:55]
	v_mfma_f32_16x16x32_bf16 v[48:51], v[170:173], v[178:181], v[48:51]
	v_mfma_f32_16x16x32_bf16 v[32:35], v[170:173], v[196:199], v[32:35]
	v_mfma_f32_16x16x32_bf16 v[36:39], v[162:165], v[196:199], v[36:39]
	v_mfma_f32_16x16x32_bf16 v[20:23], v[162:165], v[218:221], v[20:23]
	v_mfma_f32_16x16x32_bf16 v[16:19], v[170:173], v[218:221], v[16:19]
	v_mfma_f32_16x16x32_bf16 v[0:3], v[170:173], v[226:229], v[0:3]
	v_mfma_f32_16x16x32_bf16 v[4:7], v[162:165], v[226:229], v[4:7]
	s_setprio 0
	s_barrier
	s_add_i32 s8, 0, 0x18000
	s_add_i32 s20, 0, 0x1c000
	v_add_u32_e32 v154, s8, v147
	v_add_u32_e32 v238, s8, v241
	v_add_u32_e32 v170, s20, v147
	v_add_u32_e32 v239, s20, v241
	ds_read_b128 v[138:141], v154
	ds_read_b128 v[142:145], v238
	ds_read_b128 v[150:153], v154 offset:2048
	ds_read_b128 v[154:157], v238 offset:2048
	ds_read_b128 v[158:161], v170
	ds_read_b128 v[162:165], v239
	ds_read_b128 v[166:169], v170 offset:2048
	ds_read_b128 v[170:173], v239 offset:2048
	s_add_u32 s12, s12, 0x80000
	s_addc_u32 s13, s13, 0
	s_mov_b32 m0, s38
	v_lshl_add_u64 v[230:231], s[12:13], 0, v[132:133]
	ds_read_b128 v[174:177], v149 offset:32768
	ds_read_b128 v[178:181], v240 offset:32768
	ds_read_b128 v[192:195], v149 offset:34816
	ds_read_b128 v[196:199], v240 offset:34816
	ds_read_b128 v[214:217], v149 offset:36864
	ds_read_b128 v[218:221], v240 offset:36864
	ds_read_b128 v[222:225], v149 offset:38912
	ds_read_b128 v[226:229], v240 offset:38912
	global_load_lds_dwordx4 v[230:231], off
	v_lshl_add_u64 v[230:231], s[12:13], 0, v[130:131]
	s_mov_b32 m0, s39
	s_nop 0
	global_load_lds_dwordx4 v[230:231], off
	s_waitcnt vmcnt(8)
	s_waitcnt lgkmcnt(0)
	s_barrier
	s_setprio 1
	s_waitcnt lgkmcnt(0)
	v_mfma_f32_16x16x32_bf16 v[124:127], v[138:141], v[174:177], v[124:127]
	v_mfma_f32_16x16x32_bf16 v[120:123], v[150:153], v[174:177], v[120:123]
	v_mfma_f32_16x16x32_bf16 v[104:107], v[150:153], v[192:195], v[104:107]
	v_mfma_f32_16x16x32_bf16 v[108:111], v[138:141], v[192:195], v[108:111]
	v_mfma_f32_16x16x32_bf16 v[92:95], v[138:141], v[214:217], v[92:95]
	v_mfma_f32_16x16x32_bf16 v[88:91], v[150:153], v[214:217], v[88:91]
	v_mfma_f32_16x16x32_bf16 v[72:75], v[150:153], v[222:225], v[72:75]
	v_mfma_f32_16x16x32_bf16 v[76:79], v[138:141], v[222:225], v[76:79]
	v_mfma_f32_16x16x32_bf16 v[124:127], v[142:145], v[178:181], v[124:127]
	v_mfma_f32_16x16x32_bf16 v[120:123], v[154:157], v[178:181], v[120:123]
	v_mfma_f32_16x16x32_bf16 v[104:107], v[154:157], v[196:199], v[104:107]
	v_mfma_f32_16x16x32_bf16 v[108:111], v[142:145], v[196:199], v[108:111]
	v_mfma_f32_16x16x32_bf16 v[92:95], v[142:145], v[218:221], v[92:95]
	v_mfma_f32_16x16x32_bf16 v[88:91], v[154:157], v[218:221], v[88:91]
	v_mfma_f32_16x16x32_bf16 v[72:75], v[154:157], v[226:229], v[72:75]
	v_mfma_f32_16x16x32_bf16 v[76:79], v[142:145], v[226:229], v[76:79]
	s_setprio 0
	s_setprio 1
	v_mfma_f32_16x16x32_bf16 v[116:119], v[158:161], v[174:177], v[116:119]
	v_mfma_f32_16x16x32_bf16 v[112:115], v[166:169], v[174:177], v[112:115]
	v_mfma_f32_16x16x32_bf16 v[96:99], v[166:169], v[192:195], v[96:99]
	v_mfma_f32_16x16x32_bf16 v[100:103], v[158:161], v[192:195], v[100:103]
	v_mfma_f32_16x16x32_bf16 v[84:87], v[158:161], v[214:217], v[84:87]
	v_mfma_f32_16x16x32_bf16 v[80:83], v[166:169], v[214:217], v[80:83]
	v_mfma_f32_16x16x32_bf16 v[64:67], v[166:169], v[222:225], v[64:67]
	v_mfma_f32_16x16x32_bf16 v[68:71], v[158:161], v[222:225], v[68:71]
	v_mfma_f32_16x16x32_bf16 v[116:119], v[162:165], v[178:181], v[116:119]
	v_mfma_f32_16x16x32_bf16 v[112:115], v[170:173], v[178:181], v[112:115]
	v_mfma_f32_16x16x32_bf16 v[96:99], v[170:173], v[196:199], v[96:99]
	v_mfma_f32_16x16x32_bf16 v[100:103], v[162:165], v[196:199], v[100:103]
	v_mfma_f32_16x16x32_bf16 v[84:87], v[162:165], v[218:221], v[84:87]
	v_mfma_f32_16x16x32_bf16 v[80:83], v[170:173], v[218:221], v[80:83]
	v_mfma_f32_16x16x32_bf16 v[64:67], v[170:173], v[226:229], v[64:67]
	v_mfma_f32_16x16x32_bf16 v[68:71], v[162:165], v[226:229], v[68:71]
	s_setprio 0
	s_barrier
	s_add_i32 s8, s8, s25
	v_lshl_add_u64 v[182:183], v[182:183], 0, s[26:27]
	s_mov_b32 m0, s8
	ds_read_b128 v[174:177], v149 offset:49152
	ds_read_b128 v[178:181], v240 offset:49152
	ds_read_b128 v[192:195], v149 offset:51200
	ds_read_b128 v[196:199], v240 offset:51200
	ds_read_b128 v[214:217], v149 offset:53248
	ds_read_b128 v[218:221], v240 offset:53248
	ds_read_b128 v[222:225], v149 offset:55296
	ds_read_b128 v[226:229], v240 offset:55296
	global_load_lds_dwordx4 v[182:183], off
	s_add_i32 m0, s8, 0x2000
	s_add_u32 s12, s44, 0x80080
	v_lshl_add_u64 v[182:183], v[186:187], 0, s[26:27]
	s_addc_u32 s13, s45, 0
	s_add_i32 s8, s20, s25
	global_load_lds_dwordx4 v[182:183], off
	v_lshl_add_u64 v[182:183], s[12:13], 0, v[184:185]
	s_mov_b32 m0, s8
	s_nop 0
	global_load_lds_dwordx4 v[182:183], off
	v_lshl_add_u64 v[182:183], s[12:13], 0, v[128:129]
	s_add_i32 m0, s8, 0x2000
	s_nop 0
	global_load_lds_dwordx4 v[182:183], off
	v_lshl_add_u64 v[182:183], v[188:189], 0, s[26:27]
	s_mov_b32 m0, s34
	s_nop 0
	global_load_lds_dwordx4 v[182:183], off
	v_lshl_add_u64 v[182:183], v[200:201], 0, s[26:27]
	s_mov_b32 m0, s35
	s_nop 0
	global_load_lds_dwordx4 v[182:183], off
	s_waitcnt vmcnt(8)
	s_waitcnt lgkmcnt(0)
	s_barrier
	s_setprio 1
	s_waitcnt lgkmcnt(0)
	v_mfma_f32_16x16x32_bf16 v[60:63], v[138:141], v[174:177], v[60:63]
	v_mfma_f32_16x16x32_bf16 v[56:59], v[150:153], v[174:177], v[56:59]
	v_mfma_f32_16x16x32_bf16 v[40:43], v[150:153], v[192:195], v[40:43]
	v_mfma_f32_16x16x32_bf16 v[44:47], v[138:141], v[192:195], v[44:47]
	v_mfma_f32_16x16x32_bf16 v[28:31], v[138:141], v[214:217], v[28:31]
	v_mfma_f32_16x16x32_bf16 v[24:27], v[150:153], v[214:217], v[24:27]
	v_mfma_f32_16x16x32_bf16 v[8:11], v[150:153], v[222:225], v[8:11]
	v_mfma_f32_16x16x32_bf16 v[12:15], v[138:141], v[222:225], v[12:15]
	v_mfma_f32_16x16x32_bf16 v[60:63], v[142:145], v[178:181], v[60:63]
	v_mfma_f32_16x16x32_bf16 v[56:59], v[154:157], v[178:181], v[56:59]
	v_mfma_f32_16x16x32_bf16 v[40:43], v[154:157], v[196:199], v[40:43]
	v_mfma_f32_16x16x32_bf16 v[44:47], v[142:145], v[196:199], v[44:47]
	v_mfma_f32_16x16x32_bf16 v[28:31], v[142:145], v[218:221], v[28:31]
	v_mfma_f32_16x16x32_bf16 v[24:27], v[154:157], v[218:221], v[24:27]
	v_mfma_f32_16x16x32_bf16 v[8:11], v[154:157], v[226:229], v[8:11]
	v_mfma_f32_16x16x32_bf16 v[12:15], v[142:145], v[226:229], v[12:15]
	s_setprio 0
	s_setprio 1
	v_mfma_f32_16x16x32_bf16 v[52:55], v[158:161], v[174:177], v[52:55]
	v_mfma_f32_16x16x32_bf16 v[48:51], v[166:169], v[174:177], v[48:51]
	v_mfma_f32_16x16x32_bf16 v[32:35], v[166:169], v[192:195], v[32:35]
	v_mfma_f32_16x16x32_bf16 v[36:39], v[158:161], v[192:195], v[36:39]
	v_mfma_f32_16x16x32_bf16 v[20:23], v[158:161], v[214:217], v[20:23]
	v_mfma_f32_16x16x32_bf16 v[16:19], v[166:169], v[214:217], v[16:19]
	v_mfma_f32_16x16x32_bf16 v[0:3], v[166:169], v[222:225], v[0:3]
	v_mfma_f32_16x16x32_bf16 v[4:7], v[158:161], v[222:225], v[4:7]
	v_mfma_f32_16x16x32_bf16 v[52:55], v[162:165], v[178:181], v[52:55]
	v_mfma_f32_16x16x32_bf16 v[48:51], v[170:173], v[178:181], v[48:51]
	v_mfma_f32_16x16x32_bf16 v[32:35], v[170:173], v[196:199], v[32:35]
	v_mfma_f32_16x16x32_bf16 v[36:39], v[162:165], v[196:199], v[36:39]
	v_mfma_f32_16x16x32_bf16 v[20:23], v[162:165], v[218:221], v[20:23]
	v_mfma_f32_16x16x32_bf16 v[16:19], v[170:173], v[218:221], v[16:19]
	v_mfma_f32_16x16x32_bf16 v[0:3], v[170:173], v[226:229], v[0:3]
	v_mfma_f32_16x16x32_bf16 v[4:7], v[162:165], v[226:229], v[4:7]
	s_setprio 0
	s_barrier
	s_add_i32 s51, s51, 2
	s_add_u32 s14, s14, 0x100
	s_addc_u32 s15, s15, 0
	s_add_u32 s49, s49, 0x100
	s_addc_u32 s50, s50, 0
	s_cmp_gt_u32 s51, 29
	s_cbranch_scc0 .LBB0_182
	s_and_b64 vcc, exec, s[62:63]
	s_cbranch_vccz .LBB0_185
	s_barrier
.LBB0_185:
	v_mov_b32_e32 v138, v146
	s_lshl_b32 s8, s16, 8
	s_add_i32 s8, s8, s96
	v_add_u32_e32 v138, s8, v138
	v_ashrrev_i32_e32 v139, 31, v138
	v_lshl_add_u64 v[140:141], v[138:139], 2, s[60:61]
	v_mov_b32_e32 v142, v246
	v_mov_b32_e32 v155, v247
	v_mov_b32_e32 v154, v248
	v_mov_b32_e32 v153, v249
	v_mov_b32_e32 v152, v250
	v_mov_b32_e32 v151, v251
	v_mov_b32_e32 v150, v252
	v_mov_b32_e32 v139, v253
	s_cmp_gt_i32 s9, 11
	s_cselect_b64 s[14:15], -1, 0
	s_cmp_lt_i32 s9, 12
	v_fmamk_f32 v140, v142, 0x3a000000, v204
	v_mul_f32_e32 v141, 0x4f800000, v140
	v_cmp_gt_f32_e32 vcc, s94, v140
	s_nop 1
	v_cndmask_b32_e32 v140, v140, v141, vcc
	v_sqrt_f32_e32 v141, v140
	s_nop 0
	v_add_u32_e32 v142, -1, v141
	v_add_u32_e32 v143, 1, v141
	v_fma_f32 v144, -v142, v141, v140
	v_fma_f32 v145, -v143, v141, v140
	v_cmp_ge_f32_e64 s[44:45], 0, v144
	s_nop 1
	v_cndmask_b32_e64 v141, v141, v142, s[44:45]
	v_cmp_lt_f32_e64 s[44:45], 0, v145
	s_nop 1
	v_cndmask_b32_e64 v141, v141, v143, s[44:45]
	v_mul_f32_e32 v142, 0x37800000, v141
	v_cndmask_b32_e32 v141, v141, v142, vcc
	v_cmp_class_f32_e32 vcc, v140, v205
	s_nop 1
	v_cndmask_b32_e32 v140, v141, v140, vcc
	v_div_scale_f32 v141, s[12:13], v140, v140, 1.0
	v_rcp_f32_e32 v142, v141
	v_div_scale_f32 v143, vcc, 1.0, v140, 1.0
	v_fma_f32 v144, -v141, v142, 1.0
	v_fmac_f32_e32 v142, v144, v142
	v_mul_f32_e32 v144, v143, v142
	v_fma_f32 v145, -v141, v144, v143
	v_fmac_f32_e32 v144, v145, v142
	v_fma_f32 v141, -v141, v144, v143
	v_div_fmas_f32 v141, v141, v142, v144
	v_div_fixup_f32 v140, v141, v140, 1.0
	v_pk_mul_f32 v[126:127], v[126:127], v[140:141] op_sel_hi:[1,0]
	v_pk_mul_f32 v[124:125], v[124:125], v[140:141] op_sel_hi:[1,0]
	v_pk_mul_f32 v[142:143], v[122:123], v[140:141] op_sel_hi:[1,0]
	v_pk_mul_f32 v[144:145], v[120:121], v[140:141] op_sel_hi:[1,0]
	s_cbranch_scc1 .LBB0_187
	v_mul_f32_e32 v120, 0xbfb8aa3b, v124
	v_mul_f32_e32 v121, 0xbfb8aa3b, v125
	v_mul_f32_e32 v122, 0xbfb8aa3b, v126
	v_mul_f32_e32 v123, 0xbfb8aa3b, v127
	v_exp_f32_e32 v120, v120
	v_exp_f32_e32 v121, v121
	v_exp_f32_e32 v122, v122
	v_exp_f32_e32 v123, v123
	v_add_f32_e32 v120, 1.0, v120
	v_add_f32_e32 v121, 1.0, v121
	v_add_f32_e32 v122, 1.0, v122
	v_add_f32_e32 v123, 1.0, v123
	v_rcp_f32_e32 v120, v120
	v_rcp_f32_e32 v121, v121
	v_rcp_f32_e32 v122, v122
	v_rcp_f32_e32 v123, v123
	v_pk_mul_f32 v[124:125], v[124:125], v[120:121]
	v_mul_f32_e32 v120, 0xbfb8aa3b, v144
	v_pk_mul_f32 v[126:127], v[126:127], v[122:123]
	v_mul_f32_e32 v121, 0xbfb8aa3b, v145
	v_mul_f32_e32 v122, 0xbfb8aa3b, v142
	v_mul_f32_e32 v123, 0xbfb8aa3b, v143
	v_exp_f32_e32 v120, v120
	v_exp_f32_e32 v121, v121
	v_exp_f32_e32 v122, v122
	v_exp_f32_e32 v123, v123
	v_add_f32_e32 v120, 1.0, v120
	v_add_f32_e32 v121, 1.0, v121
	v_add_f32_e32 v122, 1.0, v122
	v_add_f32_e32 v123, 1.0, v123
	v_rcp_f32_e32 v120, v120
	v_rcp_f32_e32 v121, v121
	v_rcp_f32_e32 v122, v122
	v_rcp_f32_e32 v123, v123
	v_pk_mul_f32 v[144:145], v[144:145], v[120:121]
	v_pk_mul_f32 v[142:143], v[142:143], v[122:123]
